# P6: the f32 x1 row stores marked non-temporal (next read is much later, in P10) so they do not displace h1, which the next phase reads
# baseline (speedup 1.0000x reference)
; DEVI float bflo(unsigned u) { return __uint_as_float(u << 16); }
; DEVI float bfhi(unsigned u) { return __uint_as_float(u & 0xffff0000u); }
; DEVI void norm1_rows(const P& p, int it) {
;     const int lane = threadIdx.x & 63, w = threadIdx.x >> 6;
;     int r[2], b[2], t[2]; const float* src[2]; const float* mod0[2];
; #pragma unroll
;     for (int q = 0; q < 2; ++q) {
;         r[q] = it * 8 + w + 4 * q; b[q] = r[q] / TPB; t[q] = r[q] - b[q] * TPB;
;         src[q] = t[q] < CTX ? p.ctx + (size_t)(b[q] * CTX + t[q]) * 1024 : p.x + (size_t)(b[q] * SEQ + t[q] - CTX) * 1024;
;         mod0[q] = (const float*)(p.ws + OFF_MODS) + (size_t)(t[q] < CTX ? 8 : b[q]) * 3072;
;     }
;     f32x4 v[2][4], xs[2][4];
;     float ss[2] = {0.f, 0.f};
; #pragma unroll
;     for (int q = 0; q < 2; ++q) {
;         const bf16_t* y = (const bf16_t*)(p.ws + OFF_E) + (size_t)r[q] * 1024;
; #pragma unroll
;         for (int i = 0; i < 4; ++i) {
;             const uint2 q_ = *(const uint2*)(y + (i * 64 + lane) * 4);
;             v[q][i] = (f32x4){bflo(q_.x), bfhi(q_.x), bflo(q_.y), bfhi(q_.y)};
;             xs[q][i] = *(const f32x4*)(src[q] + (i * 64 + lane) * 4);
;         }
;     }
; #pragma unroll
;     for (int q = 0; q < 2; ++q) {
; #pragma unroll
;         for (int i = 0; i < 4; ++i) ss[q] += sumsq4(v[q][i]);
.LBB0_1253:
	v_mul_hi_i32 v0, v44, s15
	v_lshrrev_b32_e32 v1, 31, v0
	v_ashrrev_i32_e32 v0, 11, v0
	v_add_u32_e32 v9, v0, v1
	v_mul_i32_i24_e32 v6, 0xffffef00, v9
	v_mad_i32_i24 v1, v9, s16, v44
	v_lshl_add_u32 v0, v9, 12, v6
	v_cmp_gt_i32_e64 s[2:3], s7, v1
	v_cmp_lt_i32_e32 vcc, s17, v1
	v_mov_b64_e32 v[2:3], s[56:57]
	v_add3_u32 v0, v44, v0, s18
	s_and_saveexec_b64 s[4:5], vcc
	s_xor_b64 s[4:5], exec, s[4:5]
	v_mov_b64_e32 v[2:3], s[52:53]
	s_or_saveexec_b64 s[4:5], s[4:5]
	v_lshl_add_u32 v5, s21, 3, v179
	v_mov_b32_e32 v4, v0
	s_xor_b64 exec, exec, s[4:5]
	v_lshlrev_b32_e32 v4, 8, v9
	v_add3_u32 v4, v6, v5, v4
	s_or_b64 exec, exec, s[4:5]
	v_add_u32_e32 v10, 4, v44
	v_mul_hi_i32 v6, v10, s15
	v_lshrrev_b32_e32 v7, 31, v6
	v_ashrrev_i32_e32 v6, 11, v6
	v_add_u32_e32 v106, v6, v7
	v_mul_i32_i24_e32 v11, 0xffffef00, v106
	v_mad_i32_i24 v59, v106, s16, v10
	v_lshl_add_u32 v8, v106, 12, v11
	v_cmp_gt_i32_e32 vcc, s7, v59
	v_cmp_lt_i32_e64 s[4:5], s17, v59
	v_mov_b64_e32 v[6:7], s[56:57]
	v_add3_u32 v58, v44, v8, s19
	s_and_saveexec_b64 s[22:23], s[4:5]
	s_xor_b64 s[4:5], exec, s[22:23]
	v_mov_b64_e32 v[6:7], s[52:53]
	s_or_saveexec_b64 s[4:5], s[4:5]
	v_mov_b32_e32 v8, v58
	s_xor_b64 exec, exec, s[4:5]
	v_add_u32_e32 v5, v5, v11
	v_lshlrev_b32_e32 v8, 8, v106
	v_add3_u32 v8, v5, v8, 4
	s_or_b64 exec, exec, s[4:5]
	v_ashrrev_i32_e32 v11, 31, v10
	v_lshlrev_b64 v[54:55], 11, v[10:11]
	v_ashrrev_i32_e32 v45, 31, v44
	v_lshl_add_u64 v[10:11], v[40:41], 0, v[54:55]
	v_lshlrev_b64 v[56:57], 11, v[44:45]
	global_load_dwordx2 v[64:65], v[10:11], off
	global_load_dwordx2 v[66:67], v[10:11], off offset:512
	global_load_dwordx2 v[70:71], v[10:11], off offset:1024
	global_load_dwordx2 v[80:81], v[10:11], off offset:1536
	v_lshl_add_u64 v[10:11], v[40:41], 0, v[56:57]
	global_load_dwordx2 v[82:83], v[10:11], off offset:512
	global_load_dwordx2 v[84:85], v[10:11], off
	global_load_dwordx2 v[92:93], v[10:11], off offset:1536
	global_load_dwordx2 v[96:97], v[10:11], off offset:1024
	v_mul_i32_i24_e32 v10, 0xc00, v9
	v_ashrrev_i32_e32 v5, 31, v4
	v_ashrrev_i32_e32 v9, 31, v8
	v_cndmask_b32_e64 v10, v10, v105, s[2:3]
	v_lshlrev_b64 v[4:5], 12, v[4:5]
	v_lshlrev_b64 v[8:9], 12, v[8:9]
	v_ashrrev_i32_e32 v11, 31, v10
	v_mov_b32_e32 v47, v33
	v_lshl_add_u64 v[2:3], v[2:3], 0, v[4:5]
	v_lshl_add_u64 v[4:5], v[6:7], 0, v[8:9]
	v_lshl_add_u64 v[60:61], v[10:11], 2, s[0:1]
	v_lshl_add_u64 v[2:3], v[2:3], 0, v[46:47]
	v_lshl_add_u64 v[16:17], v[4:5], 0, v[46:47]
	v_lshl_add_u64 v[62:63], v[60:61], 0, s[8:9]
	global_load_dwordx4 v[108:111], v[34:35], off
	global_load_dwordx4 v[112:115], v[2:3], off
	global_load_dwordx4 v[8:11], v[2:3], off offset:1024
	global_load_dwordx4 v[12:15], v[2:3], off offset:2048
	global_load_dwordx4 v[4:7], v[2:3], off offset:3072
	global_load_dwordx4 v[24:27], v[16:17], off
	global_load_dwordx4 v[28:31], v[16:17], off offset:1024
	global_load_dwordx4 v[20:23], v[16:17], off offset:2048
	s_nop 0
	global_load_dwordx4 v[16:19], v[16:17], off offset:3072
	v_lshl_add_u64 v[2:3], v[62:63], 0, v[46:47]
	global_load_dwordx4 v[116:119], v[2:3], off
	v_lshl_add_u64 v[168:169], v[60:61], 0, v[46:47]
	v_lshl_add_u64 v[170:171], v[168:169], 0, s[8:9]
	v_lshl_add_u64 v[218:219], v[168:169], 0, s[10:11]
	v_lshl_add_u64 v[220:221], v[168:169], 0, s[12:13]
	global_load_dwordx4 v[120:123], v[34:35], off
	global_load_dwordx4 v[136:139], v[170:171], off
	global_load_dwordx4 v[124:127], v[34:35], off offset:1024
	global_load_dwordx4 v[140:143], v[170:171], off offset:1024
	global_load_dwordx4 v[128:131], v[34:35], off offset:2048
	global_load_dwordx4 v[144:147], v[170:171], off offset:2048
	global_load_dwordx4 v[132:135], v[34:35], off offset:3072
	global_load_dwordx4 v[148:151], v[170:171], off offset:3072
	global_load_dwordx4 v[152:155], v[38:39], off
	global_load_dwordx4 v[184:187], v[220:221], off
	global_load_dwordx4 v[200:203], v[218:219], off
	global_load_dwordx4 v[156:159], v[38:39], off offset:1024
	global_load_dwordx4 v[188:191], v[220:221], off offset:1024
	global_load_dwordx4 v[204:207], v[218:219], off offset:1024
	global_load_dwordx4 v[160:163], v[38:39], off offset:2048
	global_load_dwordx4 v[192:195], v[220:221], off offset:2048
	global_load_dwordx4 v[208:211], v[218:219], off offset:2048
	global_load_dwordx4 v[164:167], v[38:39], off offset:3072
	global_load_dwordx4 v[196:199], v[220:221], off offset:3072
	global_load_dwordx4 v[212:215], v[218:219], off offset:3072
	v_cmp_lt_i32_e64 s[2:3], s17, v1
	v_ashrrev_i32_e32 v1, 31, v0
	s_waitcnt vmcnt(37)
	v_lshlrev_b32_e32 v78, 16, v64
	v_and_b32_e32 v79, 0xffff0000, v64
	s_waitcnt vmcnt(33)
	v_and_b32_e32 v89, 0xffff0000, v82
	s_waitcnt vmcnt(32)
	v_and_b32_e32 v88, 0xffff0000, v84
	v_lshlrev_b32_e32 v76, 16, v65
	v_and_b32_e32 v77, 0xffff0000, v65
	v_lshlrev_b32_e32 v72, 16, v66
	v_and_b32_e32 v73, 0xffff0000, v66
	v_lshlrev_b32_e32 v74, 16, v67
	v_and_b32_e32 v75, 0xffff0000, v67
	v_lshlrev_b32_e32 v64, 16, v80
	v_and_b32_e32 v65, 0xffff0000, v80
	v_lshlrev_b32_e32 v66, 16, v81
	v_and_b32_e32 v67, 0xffff0000, v81
	v_lshlrev_b32_e32 v91, 16, v82
	v_lshlrev_b32_e32 v90, 16, v84
	s_waitcnt vmcnt(31)
	v_and_b32_e32 v81, 0xffff0000, v92
	s_waitcnt vmcnt(30)
; DEVI void norm1_rows(const P& p, int it) {
;     ...
; #pragma unroll
;     for (int q = 0; q < 2; ++q) {
; #pragma unroll
;         for (int i = 0; i < 4; ++i) ss[q] += sumsq4(v[q][i]);
;         ss[q] = wave_sum(ss[q]);
;     }
;     float ss2[2] = {0.f, 0.f};
; #pragma unroll
;     for (int q = 0; q < 2; ++q) {
;         const float rstd = rsqrtf(ss[q] * (1.0f / 1024.0f) + 1e-6f);
; #pragma unroll
;         for (int i = 0; i < 4; ++i) {
;             const int col = (i * 64 + lane) * 4;
;             const f32x4 g = *(const f32x4*)(p.g_post0 + col), gt = *(const f32x4*)(mod0[q] + 2048 + col);
;             v[q][i] = xs[q][i] + gt * (v[q][i] * rstd * g);
;             ss2[q] += sumsq4(v[q][i]);
;             if (t[q] >= CTX) *(f32x4*)(p.out + (size_t)(b[q] * SEQ + t[q] - CTX) * 1024 + col) = v[q][i];
;         }
;         ss2[q] = wave_sum(ss2[q]);
	v_and_b32_e32 v80, 0xffff0000, v96
	v_pk_mul_f32 v[2:3], v[88:89], v[88:89]
	v_lshlrev_b32_e32 v99, 16, v83
	v_lshlrev_b32_e32 v98, 16, v85
	v_and_b32_e32 v95, 0xffff0000, v83
	v_and_b32_e32 v94, 0xffff0000, v85
	v_lshlrev_b32_e32 v83, 16, v92
	v_lshlrev_b32_e32 v82, 16, v96
	v_lshlrev_b32_e32 v87, 16, v93
	v_and_b32_e32 v85, 0xffff0000, v93
	v_pk_mul_f32 v[92:93], v[80:81], v[80:81]
	v_pk_fma_f32 v[2:3], v[90:91], v[90:91], v[2:3]
	v_lshlrev_b32_e32 v86, 16, v97
	v_pk_fma_f32 v[92:93], v[82:83], v[82:83], v[92:93]
	v_pk_fma_f32 v[2:3], v[98:99], v[98:99], v[2:3]
	v_and_b32_e32 v84, 0xffff0000, v97
	v_pk_fma_f32 v[92:93], v[86:87], v[86:87], v[92:93]
	v_pk_fma_f32 v[2:3], v[94:95], v[94:95], v[2:3]
	v_pk_fma_f32 v[92:93], v[84:85], v[84:85], v[92:93]
	v_add_f32_e32 v2, v2, v3
	v_add_f32_e32 v2, v2, v92
	v_add_f32_e32 v2, v2, v93
	ds_bpermute_b32 v3, v49, v2
	v_mul_f32_e32 v45, v79, v79
	v_mul_f32_e32 v47, v73, v73
	v_fmac_f32_e32 v45, v78, v78
	v_fmac_f32_e32 v47, v72, v72
	s_waitcnt lgkmcnt(0)
	v_add_f32_e32 v2, v2, v3
	v_and_b32_e32 v69, 0xffff0000, v70
	v_fmac_f32_e32 v45, v76, v76
	v_fmac_f32_e32 v47, v74, v74
	ds_bpermute_b32 v3, v100, v2
	v_lshlrev_b32_e32 v68, 16, v70
	v_mul_f32_e32 v51, v69, v69
	v_fmac_f32_e32 v45, v77, v77
	v_fmac_f32_e32 v47, v75, v75
	v_lshlrev_b32_e32 v70, 16, v71
	v_fmac_f32_e32 v51, v68, v68
	v_add_f32_e32 v45, v45, v47
	v_mul_f32_e32 v47, v65, v65
	v_and_b32_e32 v71, 0xffff0000, v71
	v_fmac_f32_e32 v51, v70, v70
	v_fmac_f32_e32 v47, v64, v64
	v_fmac_f32_e32 v51, v71, v71
	v_fmac_f32_e32 v47, v66, v66
	v_add_f32_e32 v45, v45, v51
	v_fmac_f32_e32 v47, v67, v67
	s_waitcnt lgkmcnt(0)
	v_add_f32_e32 v2, v2, v3
	v_add_f32_e32 v45, v45, v47
	ds_bpermute_b32 v3, v101, v2
	ds_bpermute_b32 v47, v49, v45
	v_lshlrev_b64 v[92:93], 12, v[0:1]
	v_mov_b32_e32 v0, v98
	v_lshl_add_u64 v[92:93], v[36:37], 0, v[92:93]
	s_waitcnt lgkmcnt(1)
	v_add_f32_e32 v2, v2, v3
	s_waitcnt lgkmcnt(0)
	v_add_f32_e32 v45, v45, v47
	ds_bpermute_b32 v3, v102, v2
	ds_bpermute_b32 v47, v100, v45
	s_waitcnt lgkmcnt(1)
	v_add_f32_e32 v2, v2, v3
	s_waitcnt lgkmcnt(0)
	v_add_f32_e32 v45, v45, v47
	ds_bpermute_b32 v3, v103, v2
	ds_bpermute_b32 v47, v101, v45
	s_waitcnt lgkmcnt(1)
	v_add_f32_e32 v2, v2, v3
	s_waitcnt lgkmcnt(0)
	v_add_f32_e32 v45, v45, v47
	ds_bpermute_b32 v3, v104, v2
	ds_bpermute_b32 v47, v102, v45
	s_waitcnt lgkmcnt(1)
	v_add_f32_e32 v1, v2, v3
	s_waitcnt lgkmcnt(0)
	v_add_f32_e32 v45, v45, v47
	v_fmamk_f32 v1, v1, 0x3a800000, v48
	ds_bpermute_b32 v47, v103, v45
	v_mul_f32_e32 v2, 0x4b800000, v1
	v_cmp_gt_f32_e64 s[4:5], s20, v1
	s_waitcnt lgkmcnt(0)
	v_add_f32_e32 v45, v45, v47
	v_cndmask_b32_e64 v1, v1, v2, s[4:5]
	v_rsq_f32_e32 v2, v1
	ds_bpermute_b32 v107, v104, v45
	v_mov_b32_e32 v1, v94
	v_mul_f32_e32 v3, 0x45800000, v2
	v_cndmask_b32_e64 v96, v2, v3, s[4:5]
	v_mov_b32_e32 v2, v90
	v_mov_b32_e32 v3, v88
	v_pk_mul_f32 v[0:1], v[96:97], v[0:1] op_sel_hi:[0,1]
	v_pk_mul_f32 v[2:3], v[96:97], v[2:3] op_sel_hi:[0,1]
	s_waitcnt vmcnt(29)
	v_pk_mul_f32 v[108:109], v[108:109], v[2:3]
	v_pk_mul_f32 v[0:1], v[110:111], v[0:1]
	s_waitcnt vmcnt(0)
	v_pk_fma_f32 v[2:3], v[118:119], v[0:1], v[114:115]
	v_pk_fma_f32 v[0:1], v[116:117], v[108:109], v[112:113]
	s_and_saveexec_b64 s[4:5], s[2:3]
	s_cbranch_execz .LBB0_1263
	global_store_dwordx4 v[92:93], v[0:3], off nt
.LBB0_1263:
	s_or_b64 exec, exec, s[4:5]
	v_mov_b32_e32 v51, v33
	v_lshl_add_u64 v[112:113], v[62:63], 0, v[50:51]
	v_mov_b32_e32 v97, v96
	v_mov_b32_e32 v94, v99
	v_mov_b32_e32 v98, v96
	v_mov_b32_e32 v99, v96
	v_mov_b32_e32 v88, v91
	v_pk_mul_f32 v[90:91], v[98:99], v[94:95]
	v_pk_mul_f32 v[88:89], v[96:97], v[88:89]
	v_pk_mul_f32 v[90:91], v[90:91], v[126:127]
	v_pk_mul_f32 v[88:89], v[88:89], v[124:125]
	v_pk_fma_f32 v[10:11], v[142:143], v[90:91], v[10:11]
	v_pk_fma_f32 v[8:9], v[140:141], v[88:89], v[8:9]
	s_and_saveexec_b64 s[4:5], s[2:3]
	s_cbranch_execz .LBB0_1265
	global_store_dwordx4 v[92:93], v[8:11], off offset:1024 nt
.LBB0_1265:
	s_or_b64 exec, exec, s[4:5]
	v_mov_b32_e32 v53, v33
	v_lshl_add_u64 v[94:95], v[62:63], 0, v[52:53]
	v_mov_b32_e32 v94, v86
	v_mov_b32_e32 v95, v84
	v_mov_b32_e32 v112, v82
	v_mov_b32_e32 v113, v80
	v_pk_mul_f32 v[94:95], v[98:99], v[94:95]
	v_pk_mul_f32 v[98:99], v[96:97], v[112:113]
	v_pk_mul_f32 v[90:91], v[94:95], v[130:131]
	v_pk_mul_f32 v[88:89], v[98:99], v[128:129]
	v_pk_fma_f32 v[14:15], v[146:147], v[90:91], v[14:15]
	v_pk_fma_f32 v[12:13], v[144:145], v[88:89], v[12:13]
	s_and_saveexec_b64 s[4:5], s[2:3]
	s_cbranch_execz .LBB0_1267
	global_store_dwordx4 v[92:93], v[12:15], off offset:2048 nt
; DEVI void norm1_rows(const P& p, int it) {
;     ...
;     float ss2[2] = {0.f, 0.f};
; #pragma unroll
;     for (int q = 0; q < 2; ++q) {
;         const float rstd = rsqrtf(ss[q] * (1.0f / 1024.0f) + 1e-6f);
; #pragma unroll
;         for (int i = 0; i < 4; ++i) {
;             const int col = (i * 64 + lane) * 4;
;             const f32x4 g = *(const f32x4*)(p.g_post0 + col), gt = *(const f32x4*)(mod0[q] + 2048 + col);
;             v[q][i] = xs[q][i] + gt * (v[q][i] * rstd * g);
;             ss2[q] += sumsq4(v[q][i]);
;             if (t[q] >= CTX) *(f32x4*)(p.out + (size_t)(b[q] * SEQ + t[q] - CTX) * 1024 + col) = v[q][i];
;         }
;         ss2[q] = wave_sum(ss2[q]);
.LBB0_1267:
	s_or_b64 exec, exec, s[4:5]
	v_lshl_add_u64 v[62:63], v[62:63], 0, v[32:33]
	v_mov_b32_e32 v84, v87
	v_mov_b32_e32 v62, v96
	v_mov_b32_e32 v63, v96
	v_mov_b32_e32 v80, v83
	v_pk_mul_f32 v[62:63], v[62:63], v[84:85]
	v_pk_mul_f32 v[80:81], v[96:97], v[80:81]
	v_pk_mul_f32 v[62:63], v[62:63], v[134:135]
	v_pk_mul_f32 v[80:81], v[80:81], v[132:133]
	v_pk_fma_f32 v[6:7], v[150:151], v[62:63], v[6:7]
	v_pk_fma_f32 v[4:5], v[148:149], v[80:81], v[4:5]
	s_and_saveexec_b64 s[4:5], s[2:3]
	s_cbranch_execz .LBB0_1269
	global_store_dwordx4 v[92:93], v[4:7], off offset:3072 nt
.LBB0_1269:
	s_or_b64 exec, exec, s[4:5]
	v_mul_i32_i24_e32 v47, 0xc00, v106
	v_cndmask_b32_e32 v62, v47, v105, vcc
	v_ashrrev_i32_e32 v63, 31, v62
	v_lshl_add_u64 v[62:63], v[62:63], 2, s[0:1]
	v_lshl_add_u64 v[80:81], v[62:63], 0, s[8:9]
	v_mov_b32_e32 v47, v33
	v_lshl_add_u64 v[82:83], v[80:81], 0, v[46:47]
	v_mul_f32_e32 v47, v1, v1
	v_mul_f32_e32 v51, v9, v9
	v_mul_f32_e32 v53, v13, v13
	v_fmac_f32_e32 v47, v0, v0
	v_fmac_f32_e32 v51, v8, v8
	v_mul_f32_e32 v82, v5, v5
	v_fmac_f32_e32 v53, v12, v12
	v_fmac_f32_e32 v47, v2, v2
	v_fmac_f32_e32 v51, v10, v10
	v_fmac_f32_e32 v82, v4, v4
	v_fmac_f32_e32 v53, v14, v14
	v_fmac_f32_e32 v47, v3, v3
	v_fmac_f32_e32 v51, v11, v11
	v_fmac_f32_e32 v82, v6, v6
	v_fmac_f32_e32 v53, v15, v15
	v_add_f32_e32 v47, v47, v51
	v_fmac_f32_e32 v82, v7, v7
	v_add_f32_e32 v47, v47, v53
	v_add_f32_e32 v47, v47, v82
	ds_bpermute_b32 v51, v49, v47
	s_waitcnt lgkmcnt(1)
	v_add_f32_e32 v45, v45, v107
	v_fmamk_f32 v45, v45, 0x3a800000, v48
	v_mul_f32_e32 v53, 0x4b800000, v45
	v_cmp_gt_f32_e64 s[2:3], s20, v45
	s_waitcnt lgkmcnt(0)
	v_add_f32_e32 v47, v47, v51
	ds_bpermute_b32 v51, v100, v47
	v_cndmask_b32_e64 v45, v45, v53, s[2:3]
	v_rsq_f32_e32 v45, v45
	v_cmp_lt_i32_e32 vcc, s17, v59
	v_ashrrev_i32_e32 v59, 31, v58
	s_waitcnt lgkmcnt(0)
	v_add_f32_e32 v47, v47, v51
	ds_bpermute_b32 v51, v101, v47
	v_mul_f32_e32 v53, 0x45800000, v45
	v_lshlrev_b64 v[92:93], 12, v[58:59]
	v_cndmask_b32_e64 v82, v45, v53, s[2:3]
	v_pk_mul_f32 v[94:95], v[82:83], v[76:77] op_sel_hi:[0,1]
	s_waitcnt lgkmcnt(0)
	v_add_f32_e32 v47, v47, v51
	ds_bpermute_b32 v51, v102, v47
	v_pk_mul_f32 v[78:79], v[82:83], v[78:79] op_sel_hi:[0,1]
	s_waitcnt lgkmcnt(0)
	v_add_f32_e32 v47, v47, v51
	ds_bpermute_b32 v51, v103, v47
	s_waitcnt lgkmcnt(0)
	v_add_f32_e32 v59, v47, v51
	ds_bpermute_b32 v77, v104, v59
	v_pk_mul_f32 v[86:87], v[94:95], v[122:123]
	v_pk_mul_f32 v[78:79], v[78:79], v[120:121]
	v_pk_fma_f32 v[26:27], v[138:139], v[86:87], v[26:27]
	v_pk_fma_f32 v[24:25], v[136:137], v[78:79], v[24:25]
	v_lshl_add_u64 v[78:79], v[36:37], 0, v[92:93]
	s_and_saveexec_b64 s[2:3], vcc
	s_cbranch_execz .LBB0_1271
	global_store_dwordx4 v[78:79], v[24:27], off nt
.LBB0_1271:
	s_or_b64 exec, exec, s[2:3]
	v_mov_b32_e32 v51, v33
	v_lshl_add_u64 v[84:85], v[80:81], 0, v[50:51]
	v_mov_b32_e32 v83, v82
	v_mov_b32_e32 v84, v82
	v_mov_b32_e32 v85, v82
	v_pk_mul_f32 v[74:75], v[84:85], v[74:75]
	v_pk_mul_f32 v[72:73], v[82:83], v[72:73]
	v_pk_mul_f32 v[74:75], v[74:75], v[126:127]
	v_pk_mul_f32 v[72:73], v[72:73], v[124:125]
	v_pk_fma_f32 v[30:31], v[142:143], v[74:75], v[30:31]
	v_pk_fma_f32 v[28:29], v[140:141], v[72:73], v[28:29]
	s_and_saveexec_b64 s[2:3], vcc
	s_cbranch_execz .LBB0_1273
	global_store_dwordx4 v[78:79], v[28:31], off offset:1024 nt
.LBB0_1273:
	s_or_b64 exec, exec, s[2:3]
	v_mov_b32_e32 v53, v33
	v_lshl_add_u64 v[86:87], v[80:81], 0, v[52:53]
	v_pk_mul_f32 v[70:71], v[84:85], v[70:71]
	v_pk_mul_f32 v[68:69], v[82:83], v[68:69]
	v_pk_mul_f32 v[70:71], v[70:71], v[130:131]
	v_pk_mul_f32 v[68:69], v[68:69], v[128:129]
	v_pk_fma_f32 v[22:23], v[146:147], v[70:71], v[22:23]
	v_pk_fma_f32 v[20:21], v[144:145], v[68:69], v[20:21]
	s_and_saveexec_b64 s[2:3], vcc
	s_cbranch_execz .LBB0_1275
	global_store_dwordx4 v[78:79], v[20:23], off offset:2048 nt
.LBB0_1275:
	s_or_b64 exec, exec, s[2:3]
	v_lshl_add_u64 v[72:73], v[80:81], 0, v[32:33]
	v_mov_b32_e32 v80, v82
	v_mov_b32_e32 v81, v82
	v_pk_mul_f32 v[64:65], v[82:83], v[64:65]
	v_pk_mul_f32 v[66:67], v[80:81], v[66:67]
	v_pk_mul_f32 v[64:65], v[64:65], v[132:133]
	v_pk_mul_f32 v[66:67], v[66:67], v[134:135]
	v_pk_fma_f32 v[16:17], v[148:149], v[64:65], v[16:17]
	v_pk_fma_f32 v[18:19], v[150:151], v[66:67], v[18:19]
	s_and_saveexec_b64 s[2:3], vcc
	s_cbranch_execz .LBB0_1252
	global_store_dwordx4 v[78:79], v[16:19], off offset:3072 nt
	s_branch .LBB0_1252
